# RG-LRU gate GEMM: skip the 6 of 8 K-tiles where the block-diagonal gate matrix is all zero (per column tile only K-tiles 2pn,2pn+1 are non-zero)
# speedup vs baseline: 1.0096x; 1.0043x over previous
; #define PG8_STAGE(bufoff, gbase, voff) do { _Pragma("unroll") for (int _i = 0; _i < 2; ++_i) \
;         __builtin_amdgcn_global_load_lds((const unsigned*)((const char*)(gbase) + (voff)[_i]), (PG8_LAS unsigned*)(lds + (bufoff) + ldsw + _i * 8192), 16, 0, 0); } while (0)
; #define PG8_WAIT_V(n) asm volatile("s_waitcnt vmcnt(" #n ")" ::: "memory")
; #define PG8_BAR __builtin_amdgcn_s_barrier()
; template <class Epi, class Sched, bool ALIGN_EPI = false, bool SP2 = false>
; __device__ __forceinline__ void gemm_phase(PG8_LAS unsigned char* lds, const Gemm g, const Sched& S, const Epi& E) {
;     ...
;     for (int i = 0; i < 2; ++i) { int R, C; stage_rc(tid * 16 + i * 8192, R, C); const int Rb = Epi::PERM ? ((R & ~31) + perm32(R & 31)) : R;
;         voffA[i] = (unsigned)(R * K + C) * 2u; voffB[i] = (unsigned)(Rb * K + C) * 2u; }
;     const size_t kstep = (size_t)(BK * 2);
;     const size_t hstep = (size_t)HALF * K * 2;
;     const size_t tstep = 2 * hstep;
;     const unsigned ldsw = (unsigned)wid * 1024u;
;     const int aoff = lds_byte(wr * 64 + fr, fq * 8), boff = lds_byte(wc * 32 + fr, fq * 8);
;     ...
;     const char* cA = (const char*)gA_ + (size_t)cur.pm * tstep; const char* cB = (const char*)gB_ + (size_t)cur.pn * tstep;
;     S.a_ready(cur);
;     if constexpr (SP2) {
;         PG8_STAGE(PG8_SB(0, 0), cB, voffB); PG8_STAGE(PG8_SB(0, 1), cB + hstep, voffB); PG8_STAGE(PG8_SA(0, 0), cA, voffA); PG8_STAGE(PG8_SA(0, 1), cA + hstep, voffA);
;         if (wr == 1) PG8_BAR;
;         PG8_WAIT_V(2); PG8_BAR;
;         PG8_STAGE(PG8_SB(1, 0), cB + kstep, voffB); PG8_STAGE(PG8_SA(1, 0), cA + kstep, voffA); PG8_STAGE(PG8_SB(1, 1), cB + hstep + kstep, voffB);
.LBB0_1023:
	v_bfe_i32 v3, v19, 27, 1
	v_lshlrev_b32_e32 v0, 4, v19
	v_lshrrev_b32_e32 v3, 22, v3
	v_add_u32_e32 v3, v0, v3
	v_and_b32_e32 v3, 0xfffffc00, v3
	v_sub_u32_e32 v3, v0, v3
	v_ashrrev_i32_e32 v2, 31, v19
	v_lshrrev_b32_e32 v4, 4, v3
	v_lshrrev_b32_e32 v2, 26, v2
	v_bitop3_b32 v3, v4, v3, 32 bitop3:0x6c
	v_add_u32_e32 v2, v19, v2
	v_ashrrev_i32_e32 v5, 31, v3
	v_ashrrev_i32_e32 v2, 6, v2
	v_lshrrev_b32_e32 v5, 26, v5
	v_lshlrev_b32_e32 v4, 3, v2
	v_add_u32_e32 v5, v3, v5
	v_and_b32_e32 v4, -16, v4
	v_ashrrev_i32_e32 v6, 6, v5
	v_lshlrev_b32_e32 v2, 5, v2
	v_add_u32_e32 v4, v6, v4
	v_and_b32_e32 v14, 32, v2
	v_and_b32_e32 v2, 0xc0, v5
	v_sub_u32_e32 v2, v3, v2
	v_lshlrev_b32_e32 v3, 1, v4
	v_lshrrev_b32_e32 v5, 2, v4
	v_and_b32_e32 v6, 3, v6
	s_mov_b32 s3, 0x7fffffe0
	v_ashrrev_i16_sdwa v2, v219, sext(v2) dst_sel:DWORD dst_unused:UNUSED_PAD src0_sel:DWORD src1_sel:BYTE_0
	v_and_b32_e32 v3, 24, v3
	v_and_b32_e32 v5, 4, v5
	v_and_or_b32 v6, v4, s3, v6
	v_bfe_i32 v15, v2, 0, 16
	v_or3_b32 v3, v6, v5, v3
	v_add_u32_e32 v2, v14, v15
	v_mul_lo_u32 v16, v4, s2
	v_mul_lo_u32 v3, v3, s2
	v_add_u32_e32 v0, 0x2000, v0
	v_add_lshl_u32 v194, v2, v16, 1
	v_add_lshl_u32 v196, v3, v2, 1
	v_ashrrev_i32_e32 v2, 31, v0
	v_lshrrev_b32_e32 v2, 22, v2
	s_add_i32 s1, s1, s16
	v_add_u32_e32 v2, v0, v2
	s_ashr_i32 s16, s1, 31
	v_ashrrev_i32_e32 v2, 10, v2
	s_lshr_b32 s16, s16, 27
	v_mul_i32_i24_e32 v3, 0x400, v2
	s_add_i32 s16, s1, s16
	v_sub_u32_e32 v0, v0, v3
	s_ashr_i32 s17, s16, 5
	s_and_b32 s16, s16, 0xffe0
	v_lshrrev_b32_e32 v3, 4, v0
	s_sub_i32 s1, s1, s16
	v_bitop3_b32 v3, v3, v0, 32 bitop3:0x6c
	s_bfe_i32 s16, s1, 0x80000
	v_ashrrev_i32_e32 v4, 31, v3
	s_bfe_u32 s16, s16, 0x3000c
	v_lshrrev_b32_e32 v4, 26, v4
	s_add_i32 s16, s1, s16
	v_lshlrev_b32_e32 v0, 3, v2
	v_add_u32_e32 v4, v3, v4
	s_bfe_i32 s18, s16, 0x80000
	s_and_b32 s16, s16, 0xf8
	v_and_b32_e32 v0, -16, v0
	v_ashrrev_i32_e32 v5, 6, v4
	s_sub_i32 s1, s1, s16
	v_readlane_b32 s12, v254, 3
	v_add_u32_e32 v6, v5, v0
	v_and_b32_e32 v5, 3, v5
	s_lshl_b32 s17, s17, 3
	s_sext_i32_i8 s1, s1
	v_readlane_b32 s14, v254, 5
	v_readlane_b32 s15, v254, 6
	v_and_or_b32 v5, v6, s3, v5
	s_ashr_i32 s3, s2, 31
	s_add_i32 s1, s17, s1
	s_lshl_b64 s[14:15], s[2:3], 9
	s_ashr_i32 s16, s1, 31
	s_mul_i32 s16, s14, s16
	s_mul_hi_u32 s17, s14, s1
	s_sext_i32_i16 s19, s18
	s_add_i32 s21, s17, s16
	s_lshr_b64 s[16:17], s[2:3], 23
	s_lshr_b32 s18, s19, 3
	s_mul_i32 s17, s16, s1
	s_add_i32 s21, s21, s17
	s_bfe_i64 s[22:23], s[18:19], 0x100000
	s_ashr_i32 s17, s19, 3
	s_mul_hi_u32 s19, s14, s17
	s_mul_i32 s22, s14, s23
	v_readlane_b32 s13, v254, 4
	s_ashr_i32 s25, s26, 6
	s_add_i32 s19, s19, s22
	s_mul_i32 s16, s16, s17
	s_ashr_i32 s24, s26, 8
	v_lshlrev_b32_e32 v0, 5, v2
	v_and_b32_e32 v2, 0xc0, v4
	s_lshl_b64 s[12:13], s[2:3], 8
	s_lshl_b32 s53, s25, 10
	s_add_i32 s19, s19, s16
	s_mul_i32 s16, s14, s17
	v_sub_u32_e32 v2, v3, v2
	v_lshlrev_b32_e32 v3, 1, v6
	v_lshrrev_b32_e32 v4, 2, v6
	s_add_u32 s46, s8, s16
	v_ashrrev_i16_sdwa v2, v219, sext(v2) dst_sel:DWORD dst_unused:UNUSED_PAD src0_sel:DWORD src1_sel:BYTE_0
	v_and_b32_e32 v3, 24, v3
	v_and_b32_e32 v4, 4, v4
	s_addc_u32 s47, s9, s19
	s_lshl_b32 s98, s17, 8
	s_add_u32 s46, s46, s98
	s_addc_u32 s47, s47, 0
	s_add_i32 s94, s53, 0
	v_and_b32_e32 v0, 32, v0
	v_bfe_i32 v17, v2, 0, 16
	v_or3_b32 v3, v5, v4, v3
	s_add_i32 m0, s94, 0x10000
	v_add_u32_e32 v2, v0, v17
	v_mul_lo_u32 v3, v3, s2
	global_load_lds_dwordx4 v196, s[46:47]
	s_add_i32 m0, s94, 0x12000
	v_add_lshl_u32 v200, v3, v2, 1
	s_add_u32 s16, s46, s12
	global_load_lds_dwordx4 v200, s[46:47]
	s_addc_u32 s17, s47, s13
	s_add_i32 m0, s94, 0x14000
	s_mul_i32 s27, s14, s1
	global_load_lds_dwordx4 v196, s[16:17]
	s_add_i32 m0, s94, 0x16000
	s_add_u32 s48, s10, s27
	v_mov_b32_e32 v197, v1
	v_mov_b32_e32 v201, v1
	s_addc_u32 s49, s11, s21
	s_add_u32 s48, s48, s98
	s_addc_u32 s49, s49, 0
	s_add_i32 s92, s94, 0x2000
	v_mul_lo_u32 v18, v6, s2
	v_lshl_add_u64 v[6:7], s[16:17], 0, v[196:197]
	v_lshl_add_u64 v[8:9], s[16:17], 0, v[200:201]
	global_load_lds_dwordx4 v200, s[16:17]
	s_mov_b32 m0, s94
	s_add_u32 s16, s48, s12
	v_add_lshl_u32 v198, v2, v18, 1
	global_load_lds_dwordx4 v194, s[48:49]
	s_mov_b32 m0, s92
	s_addc_u32 s17, s49, s13
	s_add_i32 s93, s94, 0x4000
	global_load_lds_dwordx4 v198, s[48:49]
	s_mov_b32 m0, s93
	s_add_i32 s33, s94, 0x6000
	global_load_lds_dwordx4 v194, s[16:17]
	s_mov_b32 m0, s33
	v_mov_b32_e32 v195, v1
	global_load_lds_dwordx4 v198, s[16:17]
	v_mov_b32_e32 v199, v1
	s_cmp_eq_u32 s24, 1
	v_lshl_add_u64 v[2:3], s[46:47], 0, v[196:197]
	v_lshl_add_u64 v[4:5], s[46:47], 0, v[200:201]
	v_lshl_add_u64 v[10:11], s[48:49], 0, v[194:195]
	v_lshl_add_u64 v[12:13], s[48:49], 0, v[198:199]
	s_cselect_b64 s[16:17], -1, 0
	s_cmp_lg_u32 s24, 1
	s_cbranch_scc1 .LBB0_1025
	s_barrier
; #define PG8_STAGE(bufoff, gbase, voff) do { _Pragma("unroll") for (int _i = 0; _i < 2; ++_i) \
;         __builtin_amdgcn_global_load_lds((const unsigned*)((const char*)(gbase) + (voff)[_i]), (PG8_LAS unsigned*)(lds + (bufoff) + ldsw + _i * 8192), 16, 0, 0); } while (0)
; #define PG8_WAIT_V(n) asm volatile("s_waitcnt vmcnt(" #n ")" ::: "memory")
; #define PG8_BAR __builtin_amdgcn_s_barrier()
; template <class Epi, class Sched, bool ALIGN_EPI = false, bool SP2 = false>
; __device__ __forceinline__ void gemm_phase(PG8_LAS unsigned char* lds, const Gemm g, const Sched& S, const Epi& E) {
;     ...
;     const bf16_t* gA_ = g.A; const bf16_t* gB_ = g.Bt; int K = g.K; asm volatile("" : "+s"(gA_), "+s"(gB_), "+s"(K)); const int nt = K / BK;
;     ...
;         PG8_STAGE(PG8_SB(1, 0), cB + kstep, voffB); PG8_STAGE(PG8_SA(1, 0), cA + kstep, voffA); PG8_STAGE(PG8_SB(1, 1), cB + hstep + kstep, voffB);
;         PG8_WAIT_V(6); PG8_BAR;
;     } else {
;         PG8_STAGE(PG8_SB(0, 0), cB, voffB); PG8_STAGE(PG8_SA(0, 0), cA, voffA); PG8_STAGE(PG8_SB(0, 1), cB + hstep, voffB); PG8_STAGE(PG8_SA(0, 1), cA + hstep, voffA);
;         if (wr == 1) PG8_BAR;
;         PG8_WAIT_V(4); PG8_BAR;
;         PG8_STAGE(PG8_SB(1, 0), cB + kstep, voffB); PG8_STAGE(PG8_SA(1, 0), cA + kstep, voffA); PG8_STAGE(PG8_SB(1, 1), cB + hstep + kstep, voffB);
;         PG8_WAIT_V(6); PG8_BAR;
.LBB0_1025:
	s_sext_i32_i8 s45, s18
	s_add_u32 s18, s4, 0x33800000
	s_addc_u32 s19, s5, 0
	s_ashr_i32 s22, s20, 1
	s_ashr_i32 s23, s22, 31
	v_readlane_b32 s76, v254, 41
	s_lshl_b64 s[20:21], s[22:23], 12
	v_readlane_b32 s78, v254, 43
	v_readlane_b32 s79, v254, 44
	s_add_u32 s20, s78, s20
	s_addc_u32 s21, s79, s21
	s_lshl_b64 s[22:23], s[22:23], 11
	s_add_u32 s4, s4, s22
	s_addc_u32 s5, s5, s23
	s_add_u32 s22, s4, 0x1e0000
	s_addc_u32 s23, s5, 0
	s_add_i32 m0, s94, 0x18000
	v_lshl_add_u64 v[2:3], v[2:3], 0, s[38:39]
	s_waitcnt vmcnt(2)
	s_barrier
	global_load_lds_dwordx4 v[2:3], off
	v_lshl_add_u64 v[2:3], v[4:5], 0, s[38:39]
	s_add_i32 m0, s94, 0x1a000
	s_add_i32 s40, s94, 0x8000
	global_load_lds_dwordx4 v[2:3], off
	v_lshl_add_u64 v[2:3], v[10:11], 0, s[38:39]
	s_mov_b32 m0, s40
	s_add_i32 s41, s94, 0xa000
	global_load_lds_dwordx4 v[2:3], off
	v_lshl_add_u64 v[2:3], v[12:13], 0, s[38:39]
	s_mov_b32 m0, s41
	v_lshrrev_b32_e32 v21, 1, v19
	global_load_lds_dwordx4 v[2:3], off
	s_add_i32 m0, s94, 0x1c000
	v_lshl_add_u64 v[2:3], v[6:7], 0, s[38:39]
	global_load_lds_dwordx4 v[2:3], off
	v_lshl_add_u64 v[2:3], v[8:9], 0, s[38:39]
	s_add_i32 m0, s94, 0x1e000
	s_lshr_b32 s3, s3, 26
	global_load_lds_dwordx4 v[2:3], off
	v_and_b32_e32 v21, 24, v21
	v_and_b32_e32 v20, 15, v19
	s_add_i32 s3, s2, s3
	v_lshlrev_b32_e32 v22, 1, v21
	v_lshlrev_b32_e32 v19, 2, v19
	s_ashr_i32 s34, s3, 6
	s_mov_b32 s34, 2
	v_lshl_or_b32 v210, s24, 6, v20
	v_lshl_or_b32 v20, v20, 6, v22
	s_lshl_b32 s3, s24, 13
	v_and_b32_e32 v19, 32, v19
	v_bitop3_b32 v22, v20, s3, v19 bitop3:0xde
	s_lshl_b32 s3, s25, 5
	s_and_b32 s3, s3, 0x60
	s_lshl_b32 s4, s3, 7
	v_add_u32_e32 v0, v18, v0
	s_cmp_gt_i32 s2, 63
	v_add_lshl_u32 v0, v0, v17, 1
	v_readlane_b32 s84, v254, 49
	v_readlane_b32 s85, v254, 50
	v_readlane_b32 s86, v254, 51
	v_readlane_b32 s87, v254, 52
	v_readlane_b32 s88, v254, 53
	v_readlane_b32 s89, v254, 54
	v_readlane_b32 s90, v254, 55
	v_readlane_b32 s91, v254, 56
	s_waitcnt vmcnt(6)
	s_cselect_b64 s[24:25], -1, 0
	s_add_i32 s42, s34, -2
	v_lshl_add_u64 v[202:203], s[12:13], 0, v[0:1]
	v_add_u32_e32 v0, v16, v14
	v_readlane_b32 s77, v254, 42
	v_readlane_b32 s82, v254, 47
	v_readlane_b32 s83, v254, 48
	s_cmpk_lt_u32 s26, 0x100
	v_add_lshl_u32 v0, v0, v15, 1
	v_readlane_b32 s84, v255, 20
	v_readlane_b32 s78, v255, 24
	v_readlane_b32 s86, v255, 26
	v_readlane_b32 s88, v255, 28
	v_readlane_b32 s90, v255, 30
	v_bitop3_b32 v212, v20, s4, v19 bitop3:0xde
	s_cselect_b64 s[26:27], -1, 0
	s_ashr_i32 s43, s51, 31
	v_or_b32_e32 v214, s3, v21
	v_lshl_add_u64 v[204:205], s[12:13], 0, v[0:1]
	s_mov_b32 s83, 0
	v_add_u32_e32 v216, 0, v22
	v_readlane_b32 s85, v255, 21
	v_readlane_b32 s79, v255, 25
	v_readlane_b32 s87, v255, 27
	v_readlane_b32 s89, v255, 29
	v_readlane_b32 s91, v255, 31
	s_movk_i32 s82, 0x400
	s_mov_b64 s[76:77], 0x28000
	v_readlane_b32 s80, v254, 45
	v_readlane_b32 s81, v254, 46
	s_barrier
	s_branch .LBB0_1028

; template <class Epi, class Sched, bool ALIGN_EPI = false, bool SP2 = false>
; __device__ __forceinline__ void gemm_phase(PG8_LAS unsigned char* lds, const Gemm g, const Sched& S, const Epi& E) {
;     ...
;         const bool has_next = S.next(ui + 1, nxt);
;         const char* nA = has_next ? (const char*)gA_ + (size_t)nxt.pm * tstep : cA; const char* nB = has_next ? (const char*)gB_ + (size_t)nxt.pn * tstep : cB;
.LBB0_1034:
	s_nop 0
	v_cndmask_b32_e64 v0, 0, 1, s[4:5]
	v_cmp_ne_u32_e64 s[2:3], 1, v0
	s_andn2_b64 vcc, exec, s[4:5]
	s_mov_b64 s[28:29], s[48:49]
	s_cbranch_vccnz .LBB0_1036
	s_ashr_i32 s4, s44, 31
	s_mul_hi_u32 s5, s14, s44
	s_mul_i32 s4, s14, s4
	s_add_i32 s4, s5, s4
	s_mul_i32 s5, s15, s44
	s_add_i32 s4, s4, s5
	s_mul_i32 s5, s14, s44
	s_add_u32 s28, s10, s5
	s_addc_u32 s29, s11, s4
	s_lshl_b32 s98, s67, 8
	s_add_u32 s28, s28, s98
	s_addc_u32 s29, s29, 0
.LBB0_1036:
	s_and_b64 vcc, exec, s[2:3]
	s_mov_b64 s[30:31], s[46:47]
	s_cbranch_vccnz .LBB0_1038
	s_ashr_i32 s4, s67, 31
	s_mul_hi_u32 s5, s14, s67
	s_mul_i32 s4, s14, s4
	s_add_i32 s4, s5, s4
	s_mul_i32 s5, s15, s67
	s_add_i32 s4, s4, s5
	s_mul_i32 s5, s14, s67
	s_add_u32 s30, s8, s5
	s_addc_u32 s31, s9, s4
	s_lshl_b32 s98, s67, 8
	s_add_u32 s30, s30, s98
	s_addc_u32 s31, s31, 0
